# LN1/LN2 row loops rewritten: next row pair prefetched, mods loaded once per pair at iteration head, paired reductions; same arithmetic
# speedup vs baseline: 1.0292x; 1.0292x over previous
.LBB0_30:
	v_readlane_b32 s16, v252, 24
	v_readlane_b32 s20, v252, 28
	v_readlane_b32 s34, v255, 5
	v_readlane_b32 s17, v252, 25
	v_readlane_b32 s21, v252, 29
	v_readlane_b32 s35, v255, 6
	s_add_u32 s16, s20, s34
	s_addc_u32 s17, s21, s35
	v_readlane_b32 s22, v252, 30
	v_writelane_b32 v255, s16, 9
	v_readlane_b32 s23, v252, 31
	v_readlane_b32 s18, v252, 26
	v_writelane_b32 v255, s17, 10
	s_add_u32 s16, s22, s34
	s_addc_u32 s17, s23, s35
	v_readlane_b32 s19, v252, 27
	v_readlane_b32 s24, v252, 32
	v_readlane_b32 s25, v252, 33
	v_readlane_b32 s26, v252, 34
	v_readlane_b32 s27, v252, 35
	v_readlane_b32 s28, v252, 36
	v_readlane_b32 s29, v252, 37
	v_readlane_b32 s30, v252, 38
	v_readlane_b32 s31, v252, 39
	v_writelane_b32 v255, s16, 11
	s_mov_b64 s[42:43], -1
	s_nop 0
	v_writelane_b32 v255, s17, 12
	v_readlane_b32 s16, v252, 40
	v_readlane_b32 s17, v252, 41
	s_add_u32 s16, s16, s34
	s_addc_u32 s17, s17, s35
	v_readlane_b32 s18, v252, 42
	v_writelane_b32 v255, s16, 13
	v_readlane_b32 s19, v252, 43
	v_readlane_b32 s20, v252, 44
	v_writelane_b32 v255, s17, 14
	s_add_u32 s16, s18, s34
	s_addc_u32 s17, s19, s35
	v_readlane_b32 s21, v252, 45
	s_add_u32 s66, s20, s34
	s_addc_u32 s67, s21, s35
	s_add_i32 s2, s0, s2
	s_and_b32 s0, s1, 1
	v_writelane_b32 v255, s16, 15
	s_bitcmp1_b32 s1, 0
	v_readlane_b32 s22, v252, 46
	v_writelane_b32 v255, s17, 16
	s_cselect_b64 s[16:17], -1, 0
	s_cmp_eq_u32 s0, 0
	s_cselect_b64 s[44:45], -1, 0
	v_writelane_b32 v255, s1, 17
	s_and_b64 s[0:1], s[44:45], exec
	v_writelane_b32 v255, s16, 18
	s_cselect_b32 s0, -3, -6
	s_add_i32 s0, s0, s2
	v_writelane_b32 v255, s17, 19
	v_writelane_b32 v255, s2, 20
	s_cmp_gt_i32 s0, -1
	v_readlane_b32 s23, v252, 47
	v_readlane_b32 s24, v252, 48
	v_readlane_b32 s25, v252, 49
	v_readlane_b32 s26, v252, 50
	v_readlane_b32 s27, v252, 51
	v_readlane_b32 s28, v252, 52
	v_readlane_b32 s29, v252, 53
	v_readlane_b32 s30, v252, 54
	v_readlane_b32 s31, v252, 55
	s_cbranch_scc0 .LBB0_281
	s_cmp_lt_i32 s0, 1
	s_cbranch_scc1 .LBB0_271
	s_cmp_lt_i32 s0, 2
	s_cbranch_scc1 .LBB0_211
	s_cmp_lg_u32 s0, 2
	s_cbranch_scc0 .LBB0_190
	s_xor_b64 s[0:1], s[40:41], -1
	s_mov_b64 s[40:41], -1
	s_and_b64 vcc, exec, s[0:1]
	s_cbranch_vccz .LBB0_185
	v_readlane_b32 s0, v255, 17
	s_add_i32 s7, s0, 1
	v_readfirstlane_b32 s0, v155
	v_mbcnt_lo_u32_b32 v0, -1, 0
	v_mbcnt_hi_u32_b32 v0, -1, v0
	s_waitcnt vmcnt(0) lgkmcnt(0)
	s_nop 0
	v_or_b32_e32 v1, s0, v0
	v_readlane_b32 s0, v252, 59
	v_readlane_b32 s1, v252, 60
	s_load_dword s2, s[0:1], 0x0
	v_ashrrev_i32_e32 v1, 5, v1
	v_and_b32_e32 v1, -2, v1
	v_readlane_b32 s0, v252, 58
	s_nop 1
	v_add_u32_e32 v32, s0, v1
	s_mov_b32 s0, 0x9000
	v_cmp_gt_i32_e32 vcc, s0, v32
	s_and_saveexec_b64 s[42:43], vcc
	s_cbranch_execz .LBB0_42
	v_readlane_b32 s0, v255, 17
	s_lshl_b32 s0, s0, 13
	s_or_b32 s28, s0, 0x1000
	v_readlane_b32 s0, v255, 9
	v_readlane_b32 s1, v255, 10
	s_add_u32 s0, s0, s28
	v_and_b32_e32 v40, 63, v0
	s_addc_u32 s1, s1, 0
	v_readlane_b32 s16, v255, 11
	v_readlane_b32 s17, v255, 12
	s_add_u32 s28, s16, s28
	v_lshlrev_b32_e32 v34, 4, v40
	s_addc_u32 s29, s17, 0
	global_load_dwordx4 v[0:3], v34, s[0:1]
	global_load_dwordx4 v[4:7], v34, s[0:1] offset:1024
	global_load_dwordx4 v[8:11], v34, s[28:29]
	global_load_dwordx4 v[12:15], v34, s[28:29] offset:1024
	global_load_dwordx4 v[16:19], v34, s[0:1] offset:2048
	global_load_dwordx4 v[20:23], v34, s[0:1] offset:3072
	global_load_dwordx4 v[24:27], v34, s[28:29] offset:2048
	global_load_dwordx4 v[28:31], v34, s[28:29] offset:3072
	v_lshlrev_b32_e32 v33, 2, v40
	v_xor_b32_e32 v77, 0x80, v33
	v_xor_b32_e32 v78, 64, v33
	v_xor_b32_e32 v79, 32, v33
	v_xor_b32_e32 v80, 16, v33
	v_xor_b32_e32 v81, 8, v33
	v_xor_b32_e32 v82, 4, v33
	v_ashrrev_i32_e32 v33, 31, v32
	s_waitcnt lgkmcnt(0)
	s_lshl_b32 s50, s2, 4
	v_readlane_b32 s68, v254, 44
	v_lshlrev_b64 v[38:39], 11, v[32:33]
	v_mov_b32_e32 v35, v153
	v_readlane_b32 s72, v254, 48
	v_readlane_b32 s73, v254, 49
	s_ashr_i32 s51, s50, 31
	v_lshl_or_b32 v38, v40, 3, v38
	v_cmp_eq_u32_e64 s[40:41], 0, v40
	s_mul_i32 s0, s7, 9
	v_lshl_add_u64 v[34:35], s[58:59], 0, v[34:35]
	v_lshl_add_u64 v[36:37], v[32:33], 3, s[72:73]
	s_lshl_b64 s[52:53], s[50:51], 3
	v_lshl_add_u64 v[38:39], s[72:73], 0, v[38:39]
	s_lshl_b64 s[54:55], s[50:51], 11
	s_mov_b64 s[88:89], 0
	v_readlane_b32 s69, v254, 45
	v_readlane_b32 s70, v254, 46
	v_readlane_b32 s71, v254, 47
	v_readlane_b32 s74, v254, 50
	v_readlane_b32 s75, v254, 51
	s_mov_b64 s[40:41], exec
	v_readfirstlane_b32 s72, v32
	v_lshlrev_b32_e32 v41, 3, v40
	v_lshlrev_b32_e32 v42, 4, v40
	v_add_u32_e32 v43, 0x1000, v42
	s_nop 3
	s_lshl_b32 s1, s72, 11
	s_add_u32 s28, s58, s1
	s_addc_u32 s29, s59, 0
	s_add_u32 s28, s28, 0xa10000
	s_addc_u32 s29, s29, 0
	global_load_dwordx2 v[44:45], v41, s[28:29] nt
	global_load_dwordx2 v[46:47], v41, s[28:29] offset:512 nt
	global_load_dwordx2 v[48:49], v41, s[28:29] offset:1024 nt
	global_load_dwordx2 v[50:51], v41, s[28:29] offset:1536 nt
	global_load_dwordx2 v[52:53], v41, s[28:29] offset:2048 nt
	global_load_dwordx2 v[54:55], v41, s[28:29] offset:2560 nt
	global_load_dwordx2 v[56:57], v41, s[28:29] offset:3072 nt
	global_load_dwordx2 v[58:59], v41, s[28:29] offset:3584 nt
	s_lshl_b32 s1, s72, 11
	s_add_u32 s54, s58, s1
	s_addc_u32 s55, s59, 0
	s_add_u32 s54, s54, 0x9a10000
	s_addc_u32 s55, s55, 0
	s_lshl_b32 s1, s72, 3
	s_add_u32 s68, s58, s1
	s_addc_u32 s69, s59, 0
	s_add_u32 s68, s68, 0x910000
	s_addc_u32 s69, s69, 0
	s_lshr_b32 s1, s72, 12
	s_add_i32 s1, s1, s0
	s_mul_i32 s1, s1, 0x6000
	s_add_u32 s70, s58, s1
	s_addc_u32 s71, s59, 0
	global_load_dwordx4 v[116:119], v42, s[70:71]
	global_load_dwordx4 v[120:123], v42, s[70:71] offset:1024
	global_load_dwordx4 v[124:127], v42, s[70:71] offset:2048
	global_load_dwordx4 v[128:131], v42, s[70:71] offset:3072
	global_load_dwordx4 v[132:135], v43, s[70:71]
	global_load_dwordx4 v[136:139], v43, s[70:71] offset:1024
	global_load_dwordx4 v[140:143], v43, s[70:71] offset:2048
	global_load_dwordx4 v[144:147], v43, s[70:71] offset:3072
	s_add_i32 s73, s72, s50
	s_cmp_gt_i32 s73, s46
	s_cbranch_scc1 .Llna_np0
	s_lshl_b32 s1, s73, 11
	s_add_u32 s28, s58, s1
	s_addc_u32 s29, s59, 0
	s_add_u32 s28, s28, 0xa10000
	s_addc_u32 s29, s29, 0
	global_load_dwordx2 v[60:61], v41, s[28:29] nt
	global_load_dwordx2 v[62:63], v41, s[28:29] offset:512 nt
	global_load_dwordx2 v[64:65], v41, s[28:29] offset:1024 nt
	global_load_dwordx2 v[66:67], v41, s[28:29] offset:1536 nt
	global_load_dwordx2 v[68:69], v41, s[28:29] offset:2048 nt
	global_load_dwordx2 v[70:71], v41, s[28:29] offset:2560 nt
	global_load_dwordx2 v[72:73], v41, s[28:29] offset:3072 nt
	global_load_dwordx2 v[74:75], v41, s[28:29] offset:3584 nt
	s_waitcnt vmcnt(16)
	s_branch .Llna_go0
.Llna_np0:
	s_waitcnt vmcnt(8)
.Llna_go0:
	v_lshlrev_b32_e32 v84, 16, v44
	v_and_b32_e32 v86, 0xffff0000, v44
	v_lshlrev_b32_e32 v88, 16, v45
	v_and_b32_e32 v90, 0xffff0000, v45
	v_lshlrev_b32_e32 v92, 16, v46
	v_and_b32_e32 v94, 0xffff0000, v46
	v_lshlrev_b32_e32 v96, 16, v47
	v_and_b32_e32 v98, 0xffff0000, v47
	v_lshlrev_b32_e32 v100, 16, v48
	v_and_b32_e32 v102, 0xffff0000, v48
	v_lshlrev_b32_e32 v104, 16, v49
	v_and_b32_e32 v106, 0xffff0000, v49
	v_lshlrev_b32_e32 v108, 16, v50
	v_and_b32_e32 v110, 0xffff0000, v50
	v_lshlrev_b32_e32 v112, 16, v51
	v_and_b32_e32 v114, 0xffff0000, v51
	v_lshlrev_b32_e32 v85, 16, v52
	v_and_b32_e32 v87, 0xffff0000, v52
	v_lshlrev_b32_e32 v89, 16, v53
	v_and_b32_e32 v91, 0xffff0000, v53
	v_lshlrev_b32_e32 v93, 16, v54
	v_and_b32_e32 v95, 0xffff0000, v54
	v_lshlrev_b32_e32 v97, 16, v55
	v_and_b32_e32 v99, 0xffff0000, v55
	v_lshlrev_b32_e32 v101, 16, v56
	v_and_b32_e32 v103, 0xffff0000, v56
	v_lshlrev_b32_e32 v105, 16, v57
	v_and_b32_e32 v107, 0xffff0000, v57
	v_lshlrev_b32_e32 v109, 16, v58
	v_and_b32_e32 v111, 0xffff0000, v58
	v_lshlrev_b32_e32 v113, 16, v59
	v_and_b32_e32 v115, 0xffff0000, v59
	v_pk_add_f32 v[32:33], v[84:85], v[86:87]
	v_pk_add_f32 v[34:35], v[92:93], v[94:95]
	v_pk_add_f32 v[36:37], v[100:101], v[102:103]
	v_pk_add_f32 v[38:39], v[108:109], v[110:111]
	v_pk_add_f32 v[32:33], v[32:33], v[88:89]
	v_pk_add_f32 v[34:35], v[34:35], v[96:97]
	v_pk_add_f32 v[36:37], v[36:37], v[104:105]
	v_pk_add_f32 v[38:39], v[38:39], v[112:113]
	v_pk_add_f32 v[32:33], v[32:33], v[90:91]
	v_pk_add_f32 v[34:35], v[34:35], v[98:99]
	v_pk_add_f32 v[36:37], v[36:37], v[106:107]
	v_pk_add_f32 v[38:39], v[38:39], v[114:115]
	v_pk_add_f32 v[148:149], v[32:33], v[34:35]
	v_pk_add_f32 v[148:149], v[148:149], v[36:37]
	v_pk_add_f32 v[148:149], v[148:149], v[38:39]
	ds_bpermute_b32 v150, v77, v148
	ds_bpermute_b32 v151, v77, v149
	s_waitcnt lgkmcnt(0)
	v_pk_add_f32 v[148:149], v[148:149], v[150:151]
	ds_bpermute_b32 v150, v78, v148
	ds_bpermute_b32 v151, v78, v149
	s_waitcnt lgkmcnt(0)
	v_pk_add_f32 v[148:149], v[148:149], v[150:151]
	ds_bpermute_b32 v150, v79, v148
	ds_bpermute_b32 v151, v79, v149
	s_waitcnt lgkmcnt(0)
	v_pk_add_f32 v[148:149], v[148:149], v[150:151]
	ds_bpermute_b32 v150, v80, v148
	ds_bpermute_b32 v151, v80, v149
	s_waitcnt lgkmcnt(0)
	v_pk_add_f32 v[148:149], v[148:149], v[150:151]
	ds_bpermute_b32 v150, v81, v148
	ds_bpermute_b32 v151, v81, v149
	s_waitcnt lgkmcnt(0)
	v_pk_add_f32 v[148:149], v[148:149], v[150:151]
	ds_bpermute_b32 v150, v82, v148
	ds_bpermute_b32 v151, v82, v149
	s_waitcnt lgkmcnt(0)
	v_pk_add_f32 v[148:149], v[148:149], v[150:151]
	v_mul_f32_e32 v148, 0x3a800000, v148
	v_mul_f32_e32 v149, 0x3a800000, v149
	v_pk_add_f32 v[84:85], v[84:85], v[148:149] neg_lo:[0,1] neg_hi:[0,1]
	v_pk_add_f32 v[86:87], v[86:87], v[148:149] neg_lo:[0,1] neg_hi:[0,1]
	v_pk_add_f32 v[88:89], v[88:89], v[148:149] neg_lo:[0,1] neg_hi:[0,1]
	v_pk_add_f32 v[90:91], v[90:91], v[148:149] neg_lo:[0,1] neg_hi:[0,1]
	v_pk_add_f32 v[92:93], v[92:93], v[148:149] neg_lo:[0,1] neg_hi:[0,1]
	v_pk_add_f32 v[94:95], v[94:95], v[148:149] neg_lo:[0,1] neg_hi:[0,1]
	v_pk_add_f32 v[96:97], v[96:97], v[148:149] neg_lo:[0,1] neg_hi:[0,1]
	v_pk_add_f32 v[98:99], v[98:99], v[148:149] neg_lo:[0,1] neg_hi:[0,1]
	v_pk_add_f32 v[100:101], v[100:101], v[148:149] neg_lo:[0,1] neg_hi:[0,1]
	v_pk_add_f32 v[102:103], v[102:103], v[148:149] neg_lo:[0,1] neg_hi:[0,1]
	v_pk_add_f32 v[104:105], v[104:105], v[148:149] neg_lo:[0,1] neg_hi:[0,1]
	v_pk_add_f32 v[106:107], v[106:107], v[148:149] neg_lo:[0,1] neg_hi:[0,1]
	v_pk_add_f32 v[108:109], v[108:109], v[148:149] neg_lo:[0,1] neg_hi:[0,1]
	v_pk_add_f32 v[110:111], v[110:111], v[148:149] neg_lo:[0,1] neg_hi:[0,1]
	v_pk_add_f32 v[112:113], v[112:113], v[148:149] neg_lo:[0,1] neg_hi:[0,1]
	v_pk_add_f32 v[114:115], v[114:115], v[148:149] neg_lo:[0,1] neg_hi:[0,1]
	v_pk_mul_f32 v[32:33], v[86:87], v[86:87]
	v_pk_mul_f32 v[34:35], v[94:95], v[94:95]
	v_pk_mul_f32 v[36:37], v[102:103], v[102:103]
	v_pk_mul_f32 v[38:39], v[110:111], v[110:111]
	v_pk_fma_f32 v[32:33], v[84:85], v[84:85], v[32:33]
	v_pk_fma_f32 v[34:35], v[92:93], v[92:93], v[34:35]
	v_pk_fma_f32 v[36:37], v[100:101], v[100:101], v[36:37]
	v_pk_fma_f32 v[38:39], v[108:109], v[108:109], v[38:39]
	v_pk_fma_f32 v[32:33], v[88:89], v[88:89], v[32:33]
	v_pk_fma_f32 v[34:35], v[96:97], v[96:97], v[34:35]
	v_pk_fma_f32 v[36:37], v[104:105], v[104:105], v[36:37]
	v_pk_fma_f32 v[38:39], v[112:113], v[112:113], v[38:39]
	v_pk_fma_f32 v[32:33], v[90:91], v[90:91], v[32:33]
	v_pk_fma_f32 v[34:35], v[98:99], v[98:99], v[34:35]
	v_pk_fma_f32 v[36:37], v[106:107], v[106:107], v[36:37]
	v_pk_fma_f32 v[38:39], v[114:115], v[114:115], v[38:39]
	v_pk_add_f32 v[150:151], v[32:33], v[34:35]
	v_pk_add_f32 v[150:151], v[36:37], v[150:151]
	v_pk_add_f32 v[150:151], v[38:39], v[150:151]
	ds_bpermute_b32 v36, v77, v150
	ds_bpermute_b32 v37, v77, v151
	s_waitcnt lgkmcnt(0)
	v_pk_add_f32 v[150:151], v[150:151], v[36:37]
	ds_bpermute_b32 v36, v78, v150
	ds_bpermute_b32 v37, v78, v151
	s_waitcnt lgkmcnt(0)
	v_pk_add_f32 v[150:151], v[150:151], v[36:37]
	ds_bpermute_b32 v36, v79, v150
	ds_bpermute_b32 v37, v79, v151
	s_waitcnt lgkmcnt(0)
	v_pk_add_f32 v[150:151], v[150:151], v[36:37]
	ds_bpermute_b32 v36, v80, v150
	ds_bpermute_b32 v37, v80, v151
	s_waitcnt lgkmcnt(0)
	v_pk_add_f32 v[150:151], v[150:151], v[36:37]
	ds_bpermute_b32 v36, v81, v150
	ds_bpermute_b32 v37, v81, v151
	s_waitcnt lgkmcnt(0)
	v_pk_add_f32 v[150:151], v[150:151], v[36:37]
	ds_bpermute_b32 v36, v82, v150
	ds_bpermute_b32 v37, v82, v151
	s_waitcnt lgkmcnt(0)
	v_pk_add_f32 v[150:151], v[150:151], v[36:37]
	v_fmamk_f32 v150, v150, 0x3a800000, v154
	v_fmamk_f32 v151, v151, 0x3a800000, v154
	v_rsq_f32_e32 v150, v150
	v_rsq_f32_e32 v151, v151
	s_nop 1
	v_mov_b32_e32 v32, v148
	v_mov_b32_e32 v33, v150
	v_mov_b32_e32 v34, v149
	v_mov_b32_e32 v35, v151
	s_mov_b64 exec, 1
	global_store_dwordx4 v153, v[32:35], s[68:69]
	s_mov_b64 exec, s[40:41]
	v_pk_mul_f32 v[84:85], v[84:85], v[150:151]
	v_pk_mul_f32 v[86:87], v[86:87], v[150:151]
	v_pk_mul_f32 v[88:89], v[88:89], v[150:151]
	v_pk_mul_f32 v[90:91], v[90:91], v[150:151]
	v_pk_mul_f32 v[92:93], v[92:93], v[150:151]
	v_pk_mul_f32 v[94:95], v[94:95], v[150:151]
	v_pk_mul_f32 v[96:97], v[96:97], v[150:151]
	v_pk_mul_f32 v[98:99], v[98:99], v[150:151]
	v_pk_mul_f32 v[100:101], v[100:101], v[150:151]
	v_pk_mul_f32 v[102:103], v[102:103], v[150:151]
	v_pk_mul_f32 v[104:105], v[104:105], v[150:151]
	v_pk_mul_f32 v[106:107], v[106:107], v[150:151]
	v_pk_mul_f32 v[108:109], v[108:109], v[150:151]
	v_pk_mul_f32 v[110:111], v[110:111], v[150:151]
	v_pk_mul_f32 v[112:113], v[112:113], v[150:151]
	v_pk_mul_f32 v[114:115], v[114:115], v[150:151]
	v_pk_fma_f32 v[84:85], v[0:1], v[84:85], v[8:9] op_sel:[0,0,0] op_sel_hi:[0,1,0]
	v_pk_fma_f32 v[86:87], v[0:1], v[86:87], v[8:9] op_sel:[1,0,1] op_sel_hi:[1,1,1]
	v_pk_fma_f32 v[88:89], v[2:3], v[88:89], v[10:11] op_sel:[0,0,0] op_sel_hi:[0,1,0]
	v_pk_fma_f32 v[90:91], v[2:3], v[90:91], v[10:11] op_sel:[1,0,1] op_sel_hi:[1,1,1]
	v_pk_fma_f32 v[92:93], v[4:5], v[92:93], v[12:13] op_sel:[0,0,0] op_sel_hi:[0,1,0]
	v_pk_fma_f32 v[94:95], v[4:5], v[94:95], v[12:13] op_sel:[1,0,1] op_sel_hi:[1,1,1]
	v_pk_fma_f32 v[96:97], v[6:7], v[96:97], v[14:15] op_sel:[0,0,0] op_sel_hi:[0,1,0]
	v_pk_fma_f32 v[98:99], v[6:7], v[98:99], v[14:15] op_sel:[1,0,1] op_sel_hi:[1,1,1]
	v_pk_fma_f32 v[100:101], v[16:17], v[100:101], v[24:25] op_sel:[0,0,0] op_sel_hi:[0,1,0]
	v_pk_fma_f32 v[102:103], v[16:17], v[102:103], v[24:25] op_sel:[1,0,1] op_sel_hi:[1,1,1]
	v_pk_fma_f32 v[104:105], v[18:19], v[104:105], v[26:27] op_sel:[0,0,0] op_sel_hi:[0,1,0]
	v_pk_fma_f32 v[106:107], v[18:19], v[106:107], v[26:27] op_sel:[1,0,1] op_sel_hi:[1,1,1]
	v_pk_fma_f32 v[108:109], v[20:21], v[108:109], v[28:29] op_sel:[0,0,0] op_sel_hi:[0,1,0]
	v_pk_fma_f32 v[110:111], v[20:21], v[110:111], v[28:29] op_sel:[1,0,1] op_sel_hi:[1,1,1]
	v_pk_fma_f32 v[112:113], v[22:23], v[112:113], v[30:31] op_sel:[0,0,0] op_sel_hi:[0,1,0]
	v_pk_fma_f32 v[114:115], v[22:23], v[114:115], v[30:31] op_sel:[1,0,1] op_sel_hi:[1,1,1]
	s_cmp_gt_i32 s73, s46
	s_cbranch_scc1 .Llna_nq0
	s_waitcnt vmcnt(9)
	s_branch .Llna_gq0

.Llna_gq0:
	v_pk_add_f32 v[132:133], v[132:133], 1.0 op_sel_hi:[1,0]
	v_pk_add_f32 v[134:135], v[134:135], 1.0 op_sel_hi:[1,0]
	v_pk_add_f32 v[136:137], v[136:137], 1.0 op_sel_hi:[1,0]
	v_pk_add_f32 v[138:139], v[138:139], 1.0 op_sel_hi:[1,0]
	v_pk_add_f32 v[140:141], v[140:141], 1.0 op_sel_hi:[1,0]
	v_pk_add_f32 v[142:143], v[142:143], 1.0 op_sel_hi:[1,0]
	v_pk_add_f32 v[144:145], v[144:145], 1.0 op_sel_hi:[1,0]
	v_pk_add_f32 v[146:147], v[146:147], 1.0 op_sel_hi:[1,0]
	v_pk_fma_f32 v[84:85], v[84:85], v[132:133], v[116:117] op_sel:[0,0,0] op_sel_hi:[1,0,0]
	v_pk_fma_f32 v[86:87], v[86:87], v[132:133], v[116:117] op_sel:[0,1,1] op_sel_hi:[1,1,1]
	v_pk_fma_f32 v[88:89], v[88:89], v[134:135], v[118:119] op_sel:[0,0,0] op_sel_hi:[1,0,0]
	v_pk_fma_f32 v[90:91], v[90:91], v[134:135], v[118:119] op_sel:[0,1,1] op_sel_hi:[1,1,1]
	v_pk_fma_f32 v[92:93], v[92:93], v[136:137], v[120:121] op_sel:[0,0,0] op_sel_hi:[1,0,0]
	v_pk_fma_f32 v[94:95], v[94:95], v[136:137], v[120:121] op_sel:[0,1,1] op_sel_hi:[1,1,1]
	v_pk_fma_f32 v[96:97], v[96:97], v[138:139], v[122:123] op_sel:[0,0,0] op_sel_hi:[1,0,0]
	v_pk_fma_f32 v[98:99], v[98:99], v[138:139], v[122:123] op_sel:[0,1,1] op_sel_hi:[1,1,1]
	v_pk_fma_f32 v[100:101], v[100:101], v[140:141], v[124:125] op_sel:[0,0,0] op_sel_hi:[1,0,0]
	v_pk_fma_f32 v[102:103], v[102:103], v[140:141], v[124:125] op_sel:[0,1,1] op_sel_hi:[1,1,1]
	v_pk_fma_f32 v[104:105], v[104:105], v[142:143], v[126:127] op_sel:[0,0,0] op_sel_hi:[1,0,0]
	v_pk_fma_f32 v[106:107], v[106:107], v[142:143], v[126:127] op_sel:[0,1,1] op_sel_hi:[1,1,1]
	v_pk_fma_f32 v[108:109], v[108:109], v[144:145], v[128:129] op_sel:[0,0,0] op_sel_hi:[1,0,0]
	v_pk_fma_f32 v[110:111], v[110:111], v[144:145], v[128:129] op_sel:[0,1,1] op_sel_hi:[1,1,1]
	v_pk_fma_f32 v[112:113], v[112:113], v[146:147], v[130:131] op_sel:[0,0,0] op_sel_hi:[1,0,0]
	v_pk_fma_f32 v[114:115], v[114:115], v[146:147], v[130:131] op_sel:[0,1,1] op_sel_hi:[1,1,1]
	v_cvt_pk_bf16_f32 v44, v84, v86
	v_cvt_pk_bf16_f32 v45, v88, v90
	v_cvt_pk_bf16_f32 v46, v92, v94
	v_cvt_pk_bf16_f32 v47, v96, v98
	v_cvt_pk_bf16_f32 v48, v100, v102
	v_cvt_pk_bf16_f32 v49, v104, v106
	v_cvt_pk_bf16_f32 v50, v108, v110
	v_cvt_pk_bf16_f32 v51, v112, v114
	v_cvt_pk_bf16_f32 v52, v85, v87
	v_cvt_pk_bf16_f32 v53, v89, v91
	v_cvt_pk_bf16_f32 v54, v93, v95
	v_cvt_pk_bf16_f32 v55, v97, v99
	v_cvt_pk_bf16_f32 v56, v101, v103
	v_cvt_pk_bf16_f32 v57, v105, v107
	v_cvt_pk_bf16_f32 v58, v109, v111
	v_cvt_pk_bf16_f32 v59, v113, v115
	global_store_dwordx2 v41, v[44:45], s[54:55]
	global_store_dwordx2 v41, v[46:47], s[54:55] offset:512
	global_store_dwordx2 v41, v[48:49], s[54:55] offset:1024
	global_store_dwordx2 v41, v[50:51], s[54:55] offset:1536
	global_store_dwordx2 v41, v[52:53], s[54:55] offset:2048
	global_store_dwordx2 v41, v[54:55], s[54:55] offset:2560
	global_store_dwordx2 v41, v[56:57], s[54:55] offset:3072
	global_store_dwordx2 v41, v[58:59], s[54:55] offset:3584
	s_cmp_gt_i32 s73, s46
	s_cbranch_scc1 .Llna_exit
	s_mov_b32 s72, s73
.Llna_loop:
	s_lshl_b32 s1, s72, 11
	s_add_u32 s54, s58, s1
	s_addc_u32 s55, s59, 0
	s_add_u32 s54, s54, 0x9a10000
	s_addc_u32 s55, s55, 0
	s_lshl_b32 s1, s72, 3
	s_add_u32 s68, s58, s1
	s_addc_u32 s69, s59, 0
	s_add_u32 s68, s68, 0x910000
	s_addc_u32 s69, s69, 0
	s_lshr_b32 s1, s72, 12
	s_add_i32 s1, s1, s0
	s_mul_i32 s1, s1, 0x6000
	s_add_u32 s70, s58, s1
	s_addc_u32 s71, s59, 0
	global_load_dwordx4 v[116:119], v42, s[70:71]
	global_load_dwordx4 v[120:123], v42, s[70:71] offset:1024
	global_load_dwordx4 v[124:127], v42, s[70:71] offset:2048
	global_load_dwordx4 v[128:131], v42, s[70:71] offset:3072
	global_load_dwordx4 v[132:135], v43, s[70:71]
	global_load_dwordx4 v[136:139], v43, s[70:71] offset:1024
	global_load_dwordx4 v[140:143], v43, s[70:71] offset:2048
	global_load_dwordx4 v[144:147], v43, s[70:71] offset:3072
	s_add_i32 s73, s72, s50
	s_cmp_gt_i32 s73, s46
	s_cbranch_scc1 .Llna_np1
	s_lshl_b32 s1, s73, 11
	s_add_u32 s28, s58, s1
	s_addc_u32 s29, s59, 0
	s_add_u32 s28, s28, 0xa10000
	s_addc_u32 s29, s29, 0
	global_load_dwordx2 v[44:45], v41, s[28:29] nt
	global_load_dwordx2 v[46:47], v41, s[28:29] offset:512 nt
	global_load_dwordx2 v[48:49], v41, s[28:29] offset:1024 nt
	global_load_dwordx2 v[50:51], v41, s[28:29] offset:1536 nt
	global_load_dwordx2 v[52:53], v41, s[28:29] offset:2048 nt
	global_load_dwordx2 v[54:55], v41, s[28:29] offset:2560 nt
	global_load_dwordx2 v[56:57], v41, s[28:29] offset:3072 nt
	global_load_dwordx2 v[58:59], v41, s[28:29] offset:3584 nt
	s_waitcnt vmcnt(25)
	s_branch .Llna_go1
.Llna_np1:
	s_waitcnt vmcnt(17)
.Llna_go1:
	v_lshlrev_b32_e32 v84, 16, v60
	v_and_b32_e32 v86, 0xffff0000, v60
	v_lshlrev_b32_e32 v88, 16, v61
	v_and_b32_e32 v90, 0xffff0000, v61
	v_lshlrev_b32_e32 v92, 16, v62
	v_and_b32_e32 v94, 0xffff0000, v62
	v_lshlrev_b32_e32 v96, 16, v63
	v_and_b32_e32 v98, 0xffff0000, v63
	v_lshlrev_b32_e32 v100, 16, v64
	v_and_b32_e32 v102, 0xffff0000, v64
	v_lshlrev_b32_e32 v104, 16, v65
	v_and_b32_e32 v106, 0xffff0000, v65
	v_lshlrev_b32_e32 v108, 16, v66
	v_and_b32_e32 v110, 0xffff0000, v66
	v_lshlrev_b32_e32 v112, 16, v67
	v_and_b32_e32 v114, 0xffff0000, v67
	v_lshlrev_b32_e32 v85, 16, v68
	v_and_b32_e32 v87, 0xffff0000, v68
	v_lshlrev_b32_e32 v89, 16, v69
	v_and_b32_e32 v91, 0xffff0000, v69
	v_lshlrev_b32_e32 v93, 16, v70
	v_and_b32_e32 v95, 0xffff0000, v70
	v_lshlrev_b32_e32 v97, 16, v71
	v_and_b32_e32 v99, 0xffff0000, v71
	v_lshlrev_b32_e32 v101, 16, v72
	v_and_b32_e32 v103, 0xffff0000, v72
	v_lshlrev_b32_e32 v105, 16, v73
	v_and_b32_e32 v107, 0xffff0000, v73
	v_lshlrev_b32_e32 v109, 16, v74
	v_and_b32_e32 v111, 0xffff0000, v74
	v_lshlrev_b32_e32 v113, 16, v75
	v_and_b32_e32 v115, 0xffff0000, v75
	v_pk_add_f32 v[32:33], v[84:85], v[86:87]
	v_pk_add_f32 v[34:35], v[92:93], v[94:95]
	v_pk_add_f32 v[36:37], v[100:101], v[102:103]
	v_pk_add_f32 v[38:39], v[108:109], v[110:111]
	v_pk_add_f32 v[32:33], v[32:33], v[88:89]
	v_pk_add_f32 v[34:35], v[34:35], v[96:97]
	v_pk_add_f32 v[36:37], v[36:37], v[104:105]
	v_pk_add_f32 v[38:39], v[38:39], v[112:113]
	v_pk_add_f32 v[32:33], v[32:33], v[90:91]
	v_pk_add_f32 v[34:35], v[34:35], v[98:99]
	v_pk_add_f32 v[36:37], v[36:37], v[106:107]
	v_pk_add_f32 v[38:39], v[38:39], v[114:115]
	v_pk_add_f32 v[148:149], v[32:33], v[34:35]
	v_pk_add_f32 v[148:149], v[148:149], v[36:37]
	v_pk_add_f32 v[148:149], v[148:149], v[38:39]
	ds_bpermute_b32 v150, v77, v148
	ds_bpermute_b32 v151, v77, v149
	s_waitcnt lgkmcnt(0)
	v_pk_add_f32 v[148:149], v[148:149], v[150:151]
	ds_bpermute_b32 v150, v78, v148
	ds_bpermute_b32 v151, v78, v149
	s_waitcnt lgkmcnt(0)
	v_pk_add_f32 v[148:149], v[148:149], v[150:151]
	ds_bpermute_b32 v150, v79, v148
	ds_bpermute_b32 v151, v79, v149
	s_waitcnt lgkmcnt(0)
	v_pk_add_f32 v[148:149], v[148:149], v[150:151]
	ds_bpermute_b32 v150, v80, v148
	ds_bpermute_b32 v151, v80, v149
	s_waitcnt lgkmcnt(0)
	v_pk_add_f32 v[148:149], v[148:149], v[150:151]
	ds_bpermute_b32 v150, v81, v148
	ds_bpermute_b32 v151, v81, v149
	s_waitcnt lgkmcnt(0)
	v_pk_add_f32 v[148:149], v[148:149], v[150:151]
	ds_bpermute_b32 v150, v82, v148
	ds_bpermute_b32 v151, v82, v149
	s_waitcnt lgkmcnt(0)
	v_pk_add_f32 v[148:149], v[148:149], v[150:151]
	v_mul_f32_e32 v148, 0x3a800000, v148
	v_mul_f32_e32 v149, 0x3a800000, v149
	v_pk_add_f32 v[84:85], v[84:85], v[148:149] neg_lo:[0,1] neg_hi:[0,1]
	v_pk_add_f32 v[86:87], v[86:87], v[148:149] neg_lo:[0,1] neg_hi:[0,1]
	v_pk_add_f32 v[88:89], v[88:89], v[148:149] neg_lo:[0,1] neg_hi:[0,1]
	v_pk_add_f32 v[90:91], v[90:91], v[148:149] neg_lo:[0,1] neg_hi:[0,1]
	v_pk_add_f32 v[92:93], v[92:93], v[148:149] neg_lo:[0,1] neg_hi:[0,1]
	v_pk_add_f32 v[94:95], v[94:95], v[148:149] neg_lo:[0,1] neg_hi:[0,1]
	v_pk_add_f32 v[96:97], v[96:97], v[148:149] neg_lo:[0,1] neg_hi:[0,1]
	v_pk_add_f32 v[98:99], v[98:99], v[148:149] neg_lo:[0,1] neg_hi:[0,1]
	v_pk_add_f32 v[100:101], v[100:101], v[148:149] neg_lo:[0,1] neg_hi:[0,1]
	v_pk_add_f32 v[102:103], v[102:103], v[148:149] neg_lo:[0,1] neg_hi:[0,1]
	v_pk_add_f32 v[104:105], v[104:105], v[148:149] neg_lo:[0,1] neg_hi:[0,1]
	v_pk_add_f32 v[106:107], v[106:107], v[148:149] neg_lo:[0,1] neg_hi:[0,1]
	v_pk_add_f32 v[108:109], v[108:109], v[148:149] neg_lo:[0,1] neg_hi:[0,1]
	v_pk_add_f32 v[110:111], v[110:111], v[148:149] neg_lo:[0,1] neg_hi:[0,1]
	v_pk_add_f32 v[112:113], v[112:113], v[148:149] neg_lo:[0,1] neg_hi:[0,1]
	v_pk_add_f32 v[114:115], v[114:115], v[148:149] neg_lo:[0,1] neg_hi:[0,1]
	v_pk_mul_f32 v[32:33], v[86:87], v[86:87]
	v_pk_mul_f32 v[34:35], v[94:95], v[94:95]
	v_pk_mul_f32 v[36:37], v[102:103], v[102:103]
	v_pk_mul_f32 v[38:39], v[110:111], v[110:111]
	v_pk_fma_f32 v[32:33], v[84:85], v[84:85], v[32:33]
	v_pk_fma_f32 v[34:35], v[92:93], v[92:93], v[34:35]
	v_pk_fma_f32 v[36:37], v[100:101], v[100:101], v[36:37]
	v_pk_fma_f32 v[38:39], v[108:109], v[108:109], v[38:39]
	v_pk_fma_f32 v[32:33], v[88:89], v[88:89], v[32:33]
	v_pk_fma_f32 v[34:35], v[96:97], v[96:97], v[34:35]
	v_pk_fma_f32 v[36:37], v[104:105], v[104:105], v[36:37]
	v_pk_fma_f32 v[38:39], v[112:113], v[112:113], v[38:39]
	v_pk_fma_f32 v[32:33], v[90:91], v[90:91], v[32:33]
	v_pk_fma_f32 v[34:35], v[98:99], v[98:99], v[34:35]
	v_pk_fma_f32 v[36:37], v[106:107], v[106:107], v[36:37]
	v_pk_fma_f32 v[38:39], v[114:115], v[114:115], v[38:39]
	v_pk_add_f32 v[150:151], v[32:33], v[34:35]
	v_pk_add_f32 v[150:151], v[36:37], v[150:151]
	v_pk_add_f32 v[150:151], v[38:39], v[150:151]
	ds_bpermute_b32 v36, v77, v150
	ds_bpermute_b32 v37, v77, v151
	s_waitcnt lgkmcnt(0)
	v_pk_add_f32 v[150:151], v[150:151], v[36:37]
	ds_bpermute_b32 v36, v78, v150
	ds_bpermute_b32 v37, v78, v151
	s_waitcnt lgkmcnt(0)
	v_pk_add_f32 v[150:151], v[150:151], v[36:37]
	ds_bpermute_b32 v36, v79, v150
	ds_bpermute_b32 v37, v79, v151
	s_waitcnt lgkmcnt(0)
	v_pk_add_f32 v[150:151], v[150:151], v[36:37]
	ds_bpermute_b32 v36, v80, v150
	ds_bpermute_b32 v37, v80, v151
	s_waitcnt lgkmcnt(0)
	v_pk_add_f32 v[150:151], v[150:151], v[36:37]
	ds_bpermute_b32 v36, v81, v150
	ds_bpermute_b32 v37, v81, v151
	s_waitcnt lgkmcnt(0)
	v_pk_add_f32 v[150:151], v[150:151], v[36:37]
	ds_bpermute_b32 v36, v82, v150
	ds_bpermute_b32 v37, v82, v151
	s_waitcnt lgkmcnt(0)
	v_pk_add_f32 v[150:151], v[150:151], v[36:37]
	v_fmamk_f32 v150, v150, 0x3a800000, v154
	v_fmamk_f32 v151, v151, 0x3a800000, v154
	v_rsq_f32_e32 v150, v150
	v_rsq_f32_e32 v151, v151
	s_nop 1
	v_mov_b32_e32 v32, v148
	v_mov_b32_e32 v33, v150
	v_mov_b32_e32 v34, v149
	v_mov_b32_e32 v35, v151
	s_mov_b64 exec, 1
	global_store_dwordx4 v153, v[32:35], s[68:69]
	s_mov_b64 exec, s[40:41]
	v_pk_mul_f32 v[84:85], v[84:85], v[150:151]
	v_pk_mul_f32 v[86:87], v[86:87], v[150:151]
	v_pk_mul_f32 v[88:89], v[88:89], v[150:151]
	v_pk_mul_f32 v[90:91], v[90:91], v[150:151]
	v_pk_mul_f32 v[92:93], v[92:93], v[150:151]
	v_pk_mul_f32 v[94:95], v[94:95], v[150:151]
	v_pk_mul_f32 v[96:97], v[96:97], v[150:151]
	v_pk_mul_f32 v[98:99], v[98:99], v[150:151]
	v_pk_mul_f32 v[100:101], v[100:101], v[150:151]
	v_pk_mul_f32 v[102:103], v[102:103], v[150:151]
	v_pk_mul_f32 v[104:105], v[104:105], v[150:151]
	v_pk_mul_f32 v[106:107], v[106:107], v[150:151]
	v_pk_mul_f32 v[108:109], v[108:109], v[150:151]
	v_pk_mul_f32 v[110:111], v[110:111], v[150:151]
	v_pk_mul_f32 v[112:113], v[112:113], v[150:151]
	v_pk_mul_f32 v[114:115], v[114:115], v[150:151]
	v_pk_fma_f32 v[84:85], v[0:1], v[84:85], v[8:9] op_sel:[0,0,0] op_sel_hi:[0,1,0]
	v_pk_fma_f32 v[86:87], v[0:1], v[86:87], v[8:9] op_sel:[1,0,1] op_sel_hi:[1,1,1]
	v_pk_fma_f32 v[88:89], v[2:3], v[88:89], v[10:11] op_sel:[0,0,0] op_sel_hi:[0,1,0]
	v_pk_fma_f32 v[90:91], v[2:3], v[90:91], v[10:11] op_sel:[1,0,1] op_sel_hi:[1,1,1]
	v_pk_fma_f32 v[92:93], v[4:5], v[92:93], v[12:13] op_sel:[0,0,0] op_sel_hi:[0,1,0]
	v_pk_fma_f32 v[94:95], v[4:5], v[94:95], v[12:13] op_sel:[1,0,1] op_sel_hi:[1,1,1]
	v_pk_fma_f32 v[96:97], v[6:7], v[96:97], v[14:15] op_sel:[0,0,0] op_sel_hi:[0,1,0]
	v_pk_fma_f32 v[98:99], v[6:7], v[98:99], v[14:15] op_sel:[1,0,1] op_sel_hi:[1,1,1]
	v_pk_fma_f32 v[100:101], v[16:17], v[100:101], v[24:25] op_sel:[0,0,0] op_sel_hi:[0,1,0]
	v_pk_fma_f32 v[102:103], v[16:17], v[102:103], v[24:25] op_sel:[1,0,1] op_sel_hi:[1,1,1]
	v_pk_fma_f32 v[104:105], v[18:19], v[104:105], v[26:27] op_sel:[0,0,0] op_sel_hi:[0,1,0]
	v_pk_fma_f32 v[106:107], v[18:19], v[106:107], v[26:27] op_sel:[1,0,1] op_sel_hi:[1,1,1]
	v_pk_fma_f32 v[108:109], v[20:21], v[108:109], v[28:29] op_sel:[0,0,0] op_sel_hi:[0,1,0]
	v_pk_fma_f32 v[110:111], v[20:21], v[110:111], v[28:29] op_sel:[1,0,1] op_sel_hi:[1,1,1]
	v_pk_fma_f32 v[112:113], v[22:23], v[112:113], v[30:31] op_sel:[0,0,0] op_sel_hi:[0,1,0]
	v_pk_fma_f32 v[114:115], v[22:23], v[114:115], v[30:31] op_sel:[1,0,1] op_sel_hi:[1,1,1]
	s_cmp_gt_i32 s73, s46
	s_cbranch_scc1 .Llna_nq1
	s_waitcnt vmcnt(9)
	s_branch .Llna_gq1

.Llna_gq1:
	v_pk_add_f32 v[132:133], v[132:133], 1.0 op_sel_hi:[1,0]
	v_pk_add_f32 v[134:135], v[134:135], 1.0 op_sel_hi:[1,0]
	v_pk_add_f32 v[136:137], v[136:137], 1.0 op_sel_hi:[1,0]
	v_pk_add_f32 v[138:139], v[138:139], 1.0 op_sel_hi:[1,0]
	v_pk_add_f32 v[140:141], v[140:141], 1.0 op_sel_hi:[1,0]
	v_pk_add_f32 v[142:143], v[142:143], 1.0 op_sel_hi:[1,0]
	v_pk_add_f32 v[144:145], v[144:145], 1.0 op_sel_hi:[1,0]
	v_pk_add_f32 v[146:147], v[146:147], 1.0 op_sel_hi:[1,0]
	v_pk_fma_f32 v[84:85], v[84:85], v[132:133], v[116:117] op_sel:[0,0,0] op_sel_hi:[1,0,0]
	v_pk_fma_f32 v[86:87], v[86:87], v[132:133], v[116:117] op_sel:[0,1,1] op_sel_hi:[1,1,1]
	v_pk_fma_f32 v[88:89], v[88:89], v[134:135], v[118:119] op_sel:[0,0,0] op_sel_hi:[1,0,0]
	v_pk_fma_f32 v[90:91], v[90:91], v[134:135], v[118:119] op_sel:[0,1,1] op_sel_hi:[1,1,1]
	v_pk_fma_f32 v[92:93], v[92:93], v[136:137], v[120:121] op_sel:[0,0,0] op_sel_hi:[1,0,0]
	v_pk_fma_f32 v[94:95], v[94:95], v[136:137], v[120:121] op_sel:[0,1,1] op_sel_hi:[1,1,1]
	v_pk_fma_f32 v[96:97], v[96:97], v[138:139], v[122:123] op_sel:[0,0,0] op_sel_hi:[1,0,0]
	v_pk_fma_f32 v[98:99], v[98:99], v[138:139], v[122:123] op_sel:[0,1,1] op_sel_hi:[1,1,1]
	v_pk_fma_f32 v[100:101], v[100:101], v[140:141], v[124:125] op_sel:[0,0,0] op_sel_hi:[1,0,0]
	v_pk_fma_f32 v[102:103], v[102:103], v[140:141], v[124:125] op_sel:[0,1,1] op_sel_hi:[1,1,1]
	v_pk_fma_f32 v[104:105], v[104:105], v[142:143], v[126:127] op_sel:[0,0,0] op_sel_hi:[1,0,0]
	v_pk_fma_f32 v[106:107], v[106:107], v[142:143], v[126:127] op_sel:[0,1,1] op_sel_hi:[1,1,1]
	v_pk_fma_f32 v[108:109], v[108:109], v[144:145], v[128:129] op_sel:[0,0,0] op_sel_hi:[1,0,0]
	v_pk_fma_f32 v[110:111], v[110:111], v[144:145], v[128:129] op_sel:[0,1,1] op_sel_hi:[1,1,1]
	v_pk_fma_f32 v[112:113], v[112:113], v[146:147], v[130:131] op_sel:[0,0,0] op_sel_hi:[1,0,0]
	v_pk_fma_f32 v[114:115], v[114:115], v[146:147], v[130:131] op_sel:[0,1,1] op_sel_hi:[1,1,1]
	v_cvt_pk_bf16_f32 v60, v84, v86
	v_cvt_pk_bf16_f32 v61, v88, v90
	v_cvt_pk_bf16_f32 v62, v92, v94
	v_cvt_pk_bf16_f32 v63, v96, v98
	v_cvt_pk_bf16_f32 v64, v100, v102
	v_cvt_pk_bf16_f32 v65, v104, v106
	v_cvt_pk_bf16_f32 v66, v108, v110
	v_cvt_pk_bf16_f32 v67, v112, v114
	v_cvt_pk_bf16_f32 v68, v85, v87
	v_cvt_pk_bf16_f32 v69, v89, v91
	v_cvt_pk_bf16_f32 v70, v93, v95
	v_cvt_pk_bf16_f32 v71, v97, v99
	v_cvt_pk_bf16_f32 v72, v101, v103
	v_cvt_pk_bf16_f32 v73, v105, v107
	v_cvt_pk_bf16_f32 v74, v109, v111
	v_cvt_pk_bf16_f32 v75, v113, v115
	global_store_dwordx2 v41, v[60:61], s[54:55]
	global_store_dwordx2 v41, v[62:63], s[54:55] offset:512
	global_store_dwordx2 v41, v[64:65], s[54:55] offset:1024
	global_store_dwordx2 v41, v[66:67], s[54:55] offset:1536
	global_store_dwordx2 v41, v[68:69], s[54:55] offset:2048
	global_store_dwordx2 v41, v[70:71], s[54:55] offset:2560
	global_store_dwordx2 v41, v[72:73], s[54:55] offset:3072
	global_store_dwordx2 v41, v[74:75], s[54:55] offset:3584
	s_cmp_gt_i32 s73, s46
	s_cbranch_scc1 .Llna_exit
	s_mov_b32 s72, s73
	s_lshl_b32 s1, s72, 11
	s_add_u32 s54, s58, s1
	s_addc_u32 s55, s59, 0
	s_add_u32 s54, s54, 0x9a10000
	s_addc_u32 s55, s55, 0
	s_lshl_b32 s1, s72, 3
	s_add_u32 s68, s58, s1
	s_addc_u32 s69, s59, 0
	s_add_u32 s68, s68, 0x910000
	s_addc_u32 s69, s69, 0
	s_lshr_b32 s1, s72, 12
	s_add_i32 s1, s1, s0
	s_mul_i32 s1, s1, 0x6000
	s_add_u32 s70, s58, s1
	s_addc_u32 s71, s59, 0
	global_load_dwordx4 v[116:119], v42, s[70:71]
	global_load_dwordx4 v[120:123], v42, s[70:71] offset:1024
	global_load_dwordx4 v[124:127], v42, s[70:71] offset:2048
	global_load_dwordx4 v[128:131], v42, s[70:71] offset:3072
	global_load_dwordx4 v[132:135], v43, s[70:71]
	global_load_dwordx4 v[136:139], v43, s[70:71] offset:1024
	global_load_dwordx4 v[140:143], v43, s[70:71] offset:2048
	global_load_dwordx4 v[144:147], v43, s[70:71] offset:3072
	s_add_i32 s73, s72, s50
	s_cmp_gt_i32 s73, s46
	s_cbranch_scc1 .Llna_np2
	s_lshl_b32 s1, s73, 11
	s_add_u32 s28, s58, s1
	s_addc_u32 s29, s59, 0
	s_add_u32 s28, s28, 0xa10000
	s_addc_u32 s29, s29, 0
	global_load_dwordx2 v[60:61], v41, s[28:29] nt
	global_load_dwordx2 v[62:63], v41, s[28:29] offset:512 nt
	global_load_dwordx2 v[64:65], v41, s[28:29] offset:1024 nt
	global_load_dwordx2 v[66:67], v41, s[28:29] offset:1536 nt
	global_load_dwordx2 v[68:69], v41, s[28:29] offset:2048 nt
	global_load_dwordx2 v[70:71], v41, s[28:29] offset:2560 nt
	global_load_dwordx2 v[72:73], v41, s[28:29] offset:3072 nt
	global_load_dwordx2 v[74:75], v41, s[28:29] offset:3584 nt
	s_waitcnt vmcnt(25)
	s_branch .Llna_go2

.Llna_gq2:
	v_pk_add_f32 v[132:133], v[132:133], 1.0 op_sel_hi:[1,0]
	v_pk_add_f32 v[134:135], v[134:135], 1.0 op_sel_hi:[1,0]
	v_pk_add_f32 v[136:137], v[136:137], 1.0 op_sel_hi:[1,0]
	v_pk_add_f32 v[138:139], v[138:139], 1.0 op_sel_hi:[1,0]
	v_pk_add_f32 v[140:141], v[140:141], 1.0 op_sel_hi:[1,0]
	v_pk_add_f32 v[142:143], v[142:143], 1.0 op_sel_hi:[1,0]
	v_pk_add_f32 v[144:145], v[144:145], 1.0 op_sel_hi:[1,0]
	v_pk_add_f32 v[146:147], v[146:147], 1.0 op_sel_hi:[1,0]
	v_pk_fma_f32 v[84:85], v[84:85], v[132:133], v[116:117] op_sel:[0,0,0] op_sel_hi:[1,0,0]
	v_pk_fma_f32 v[86:87], v[86:87], v[132:133], v[116:117] op_sel:[0,1,1] op_sel_hi:[1,1,1]
	v_pk_fma_f32 v[88:89], v[88:89], v[134:135], v[118:119] op_sel:[0,0,0] op_sel_hi:[1,0,0]
	v_pk_fma_f32 v[90:91], v[90:91], v[134:135], v[118:119] op_sel:[0,1,1] op_sel_hi:[1,1,1]
	v_pk_fma_f32 v[92:93], v[92:93], v[136:137], v[120:121] op_sel:[0,0,0] op_sel_hi:[1,0,0]
	v_pk_fma_f32 v[94:95], v[94:95], v[136:137], v[120:121] op_sel:[0,1,1] op_sel_hi:[1,1,1]
	v_pk_fma_f32 v[96:97], v[96:97], v[138:139], v[122:123] op_sel:[0,0,0] op_sel_hi:[1,0,0]
	v_pk_fma_f32 v[98:99], v[98:99], v[138:139], v[122:123] op_sel:[0,1,1] op_sel_hi:[1,1,1]
	v_pk_fma_f32 v[100:101], v[100:101], v[140:141], v[124:125] op_sel:[0,0,0] op_sel_hi:[1,0,0]
	v_pk_fma_f32 v[102:103], v[102:103], v[140:141], v[124:125] op_sel:[0,1,1] op_sel_hi:[1,1,1]
	v_pk_fma_f32 v[104:105], v[104:105], v[142:143], v[126:127] op_sel:[0,0,0] op_sel_hi:[1,0,0]
	v_pk_fma_f32 v[106:107], v[106:107], v[142:143], v[126:127] op_sel:[0,1,1] op_sel_hi:[1,1,1]
	v_pk_fma_f32 v[108:109], v[108:109], v[144:145], v[128:129] op_sel:[0,0,0] op_sel_hi:[1,0,0]
	v_pk_fma_f32 v[110:111], v[110:111], v[144:145], v[128:129] op_sel:[0,1,1] op_sel_hi:[1,1,1]
	v_pk_fma_f32 v[112:113], v[112:113], v[146:147], v[130:131] op_sel:[0,0,0] op_sel_hi:[1,0,0]
	v_pk_fma_f32 v[114:115], v[114:115], v[146:147], v[130:131] op_sel:[0,1,1] op_sel_hi:[1,1,1]
	v_cvt_pk_bf16_f32 v44, v84, v86
	v_cvt_pk_bf16_f32 v45, v88, v90
	v_cvt_pk_bf16_f32 v46, v92, v94
	v_cvt_pk_bf16_f32 v47, v96, v98
	v_cvt_pk_bf16_f32 v48, v100, v102
	v_cvt_pk_bf16_f32 v49, v104, v106
	v_cvt_pk_bf16_f32 v50, v108, v110
	v_cvt_pk_bf16_f32 v51, v112, v114
	v_cvt_pk_bf16_f32 v52, v85, v87
	v_cvt_pk_bf16_f32 v53, v89, v91
	v_cvt_pk_bf16_f32 v54, v93, v95
	v_cvt_pk_bf16_f32 v55, v97, v99
	v_cvt_pk_bf16_f32 v56, v101, v103
	v_cvt_pk_bf16_f32 v57, v105, v107
	v_cvt_pk_bf16_f32 v58, v109, v111
	v_cvt_pk_bf16_f32 v59, v113, v115
	global_store_dwordx2 v41, v[44:45], s[54:55]
	global_store_dwordx2 v41, v[46:47], s[54:55] offset:512
	global_store_dwordx2 v41, v[48:49], s[54:55] offset:1024
	global_store_dwordx2 v41, v[50:51], s[54:55] offset:1536
	global_store_dwordx2 v41, v[52:53], s[54:55] offset:2048
	global_store_dwordx2 v41, v[54:55], s[54:55] offset:2560
	global_store_dwordx2 v41, v[56:57], s[54:55] offset:3072
	global_store_dwordx2 v41, v[58:59], s[54:55] offset:3584
	s_cmp_gt_i32 s73, s46
	s_cbranch_scc1 .Llna_exit
	s_mov_b32 s72, s73
	s_branch .Llna_loop
.Llna_exit:
.LBB0_42:
	s_or_b64 exec, exec, s[42:43]
	v_readfirstlane_b32 s0, v155
	s_andn2_b32 s0, s0, 63
	s_waitcnt lgkmcnt(0)
	s_barrier
	v_mbcnt_lo_u32_b32 v2, -1, 0
	v_mbcnt_hi_u32_b32 v2, -1, v2
	s_mov_b32 s43, s3
	v_or_b32_e32 v4, s0, v2
	v_cmp_eq_u32_e32 vcc, 0, v4
	s_barrier
	s_and_saveexec_b64 s[40:41], vcc
	s_cbranch_execz .LBB0_48
	s_lshl_b32 s0, s7, 9
	s_and_b32 s0, s0, 0x400
	v_readlane_b32 s16, v255, 18
	s_add_u32 s1, s58, 0xe210000
	v_readlane_b32 s17, v255, 19
	s_addc_u32 s39, s59, 0
	s_andn2_b64 vcc, exec, s[16:17]
	s_mov_b64 s[72:73], -1
	s_cbranch_vccnz .LBB0_45
	s_mul_i32 s29, s0, 0x1800
	v_readlane_b32 s16, v254, 60
	s_add_u32 s29, s16, s29
	v_readlane_b32 s16, v254, 61
	s_addc_u32 s33, s16, 0
	v_readlane_b32 s16, v254, 10
	v_mov_b32_e32 v6, s29
	v_mov_b32_e32 v7, s33
	v_mov_b32_e32 v8, s1
	v_mov_b32_e32 v9, s39
	v_mov_b32_e32 v0, s16
	v_readlane_b32 s16, v254, 11
	ds_write_b128 v0, v[6:9]
	s_add_i32 s68, s43, 0x400
	v_mov_b32_e32 v0, s16
	v_readlane_b32 s16, v254, 12
	s_add_i32 s34, s43, 0x600
	s_add_i32 s35, s43, 3
	s_add_i32 s51, s43, 0x280
	s_add_i32 s50, s43, 0x180
	v_mov_b32_e32 v3, s16
	s_lshl_b32 s29, s0, 12
	v_readlane_b32 s16, v254, 62
	v_mov_b32_e32 v6, s34
	v_mov_b32_e32 v8, s34
	v_readlane_b32 s17, v254, 63
	s_add_u32 s34, s16, s29
	v_mov_b32_e32 v9, s35
	s_addc_u32 s35, s17, 0
	v_mov_b32_e32 v7, s68
	s_add_u32 s36, s58, 0xe610000
	ds_write_b128 v0, v[6:9]
	v_mov_b32_e32 v0, s43
	v_mov_b32_e32 v1, s50
	s_addc_u32 s37, s59, 0
	v_readlane_b32 s16, v254, 13
	ds_write_b64 v3, v[0:1]
	v_mov_b64_e32 v[0:1], s[34:35]
	v_mov_b32_e32 v3, s16
	v_mov_b64_e32 v[6:7], s[36:37]
	s_add_i32 s70, s43, 1
	s_add_i32 s53, s43, 2
	s_mov_b32 s71, s51
	s_mov_b64 s[72:73], 0
	s_mov_b64 s[54:55], s[50:51]
	ds_write2_b64 v3, v[0:1], v[6:7] offset1:1

.LBB0_271:
	s_andn2_b64 vcc, exec, s[42:43]
	s_cbranch_vccnz .LBB0_280
	v_readfirstlane_b32 s0, v155
	v_mbcnt_lo_u32_b32 v0, -1, 0
	v_mbcnt_hi_u32_b32 v0, -1, v0
	s_waitcnt vmcnt(0) lgkmcnt(0)
	s_nop 0
	v_or_b32_e32 v1, s0, v0
	v_ashrrev_i32_e32 v1, 5, v1
	v_and_b32_e32 v1, -2, v1
	v_readlane_b32 s0, v252, 58
	s_nop 1
	v_add_u32_e32 v32, s0, v1
	s_mov_b32 s0, 0x9000
	v_cmp_gt_i32_e32 vcc, s0, v32
	s_and_saveexec_b64 s[42:43], vcc
	s_cbranch_execz .LBB0_279
	v_readlane_b32 s7, v255, 17
	s_lshl_b32 s2, s7, 13
	v_readlane_b32 s0, v255, 9
	v_readlane_b32 s1, v255, 10
	s_add_u32 s0, s0, s2
	v_and_b32_e32 v40, 63, v0
	s_addc_u32 s1, s1, 0
	v_readlane_b32 s16, v255, 11
	v_readlane_b32 s17, v255, 12
	s_add_u32 s28, s16, s2
	v_lshlrev_b32_e32 v34, 4, v40
	s_addc_u32 s29, s17, 0
	s_waitcnt lgkmcnt(0)
	global_load_dwordx4 v[0:3], v34, s[0:1]
	global_load_dwordx4 v[4:7], v34, s[0:1] offset:1024
	global_load_dwordx4 v[8:11], v34, s[28:29]
	global_load_dwordx4 v[12:15], v34, s[28:29] offset:1024
	global_load_dwordx4 v[16:19], v34, s[0:1] offset:2048
	global_load_dwordx4 v[20:23], v34, s[0:1] offset:3072
	global_load_dwordx4 v[24:27], v34, s[28:29] offset:2048
	global_load_dwordx4 v[28:31], v34, s[28:29] offset:3072
	v_readlane_b32 s0, v252, 59
	v_readlane_b32 s1, v252, 60
	s_load_dword s1, s[0:1], 0x0
	v_lshlrev_b32_e32 v33, 2, v40
	v_xor_b32_e32 v77, 0x80, v33
	v_xor_b32_e32 v78, 64, v33
	v_xor_b32_e32 v79, 32, v33
	v_xor_b32_e32 v80, 16, v33
	v_xor_b32_e32 v81, 8, v33
	v_xor_b32_e32 v82, 4, v33
	v_ashrrev_i32_e32 v33, 31, v32
	s_waitcnt lgkmcnt(0)
	s_lshl_b32 s44, s1, 4
	v_readlane_b32 s68, v254, 44
	v_lshlrev_b64 v[38:39], 11, v[32:33]
	v_mov_b32_e32 v35, v153
	v_readlane_b32 s72, v254, 48
	v_readlane_b32 s73, v254, 49
	s_ashr_i32 s45, s44, 31
	v_lshl_or_b32 v38, v40, 3, v38
	v_cmp_eq_u32_e64 s[40:41], 0, v40
	s_mul_i32 s0, s7, 9
	v_lshl_add_u64 v[34:35], s[58:59], 0, v[34:35]
	v_lshl_add_u64 v[36:37], v[32:33], 3, s[72:73]
	s_lshl_b64 s[50:51], s[44:45], 3
	v_lshl_add_u64 v[38:39], s[72:73], 0, v[38:39]
	s_lshl_b64 s[52:53], s[44:45], 11
	s_mov_b64 s[54:55], 0
	v_readlane_b32 s69, v254, 45
	v_readlane_b32 s70, v254, 46
	v_readlane_b32 s71, v254, 47
	v_readlane_b32 s74, v254, 50
	v_readlane_b32 s75, v254, 51
	s_mov_b64 s[40:41], exec
	v_readfirstlane_b32 s72, v32
	v_lshlrev_b32_e32 v41, 3, v40
	v_lshlrev_b32_e32 v42, 4, v40
	v_add_u32_e32 v43, 0x1000, v42
	s_nop 3
	s_lshl_b32 s1, s72, 11
	s_add_u32 s28, s58, s1
	s_addc_u32 s29, s59, 0
	s_add_u32 s28, s28, 0xa10000
	s_addc_u32 s29, s29, 0
	global_load_dwordx2 v[44:45], v41, s[28:29] nt
	global_load_dwordx2 v[46:47], v41, s[28:29] offset:512 nt
	global_load_dwordx2 v[48:49], v41, s[28:29] offset:1024 nt
	global_load_dwordx2 v[50:51], v41, s[28:29] offset:1536 nt
	global_load_dwordx2 v[52:53], v41, s[28:29] offset:2048 nt
	global_load_dwordx2 v[54:55], v41, s[28:29] offset:2560 nt
	global_load_dwordx2 v[56:57], v41, s[28:29] offset:3072 nt
	global_load_dwordx2 v[58:59], v41, s[28:29] offset:3584 nt
	s_lshl_b32 s1, s72, 11
	s_add_u32 s54, s58, s1
	s_addc_u32 s55, s59, 0
	s_add_u32 s54, s54, 0x9a10000
	s_addc_u32 s55, s55, 0
	s_lshl_b32 s1, s72, 3
	s_add_u32 s68, s58, s1
	s_addc_u32 s69, s59, 0
	s_add_u32 s68, s68, 0x910000
	s_addc_u32 s69, s69, 0
	s_lshr_b32 s1, s72, 12
	s_add_i32 s1, s1, s0
	s_mul_i32 s1, s1, 0x6000
	s_add_i32 s1, s1, 0x3000
	s_add_u32 s70, s58, s1
	s_addc_u32 s71, s59, 0
	global_load_dwordx4 v[116:119], v42, s[70:71]
	global_load_dwordx4 v[120:123], v42, s[70:71] offset:1024
	global_load_dwordx4 v[124:127], v42, s[70:71] offset:2048
	global_load_dwordx4 v[128:131], v42, s[70:71] offset:3072
	global_load_dwordx4 v[132:135], v43, s[70:71]
	global_load_dwordx4 v[136:139], v43, s[70:71] offset:1024
	global_load_dwordx4 v[140:143], v43, s[70:71] offset:2048
	global_load_dwordx4 v[144:147], v43, s[70:71] offset:3072
	s_add_i32 s73, s72, s44
	s_cmp_gt_i32 s73, s46
	s_cbranch_scc1 .Llnb_np0
	s_lshl_b32 s1, s73, 11
	s_add_u32 s28, s58, s1
	s_addc_u32 s29, s59, 0
	s_add_u32 s28, s28, 0xa10000
	s_addc_u32 s29, s29, 0
	global_load_dwordx2 v[60:61], v41, s[28:29] nt
	global_load_dwordx2 v[62:63], v41, s[28:29] offset:512 nt
	global_load_dwordx2 v[64:65], v41, s[28:29] offset:1024 nt
	global_load_dwordx2 v[66:67], v41, s[28:29] offset:1536 nt
	global_load_dwordx2 v[68:69], v41, s[28:29] offset:2048 nt
	global_load_dwordx2 v[70:71], v41, s[28:29] offset:2560 nt
	global_load_dwordx2 v[72:73], v41, s[28:29] offset:3072 nt
	global_load_dwordx2 v[74:75], v41, s[28:29] offset:3584 nt
	s_waitcnt vmcnt(16)
	s_branch .Llnb_go0

.Llnb_loop:
	s_lshl_b32 s1, s72, 11
	s_add_u32 s54, s58, s1
	s_addc_u32 s55, s59, 0
	s_add_u32 s54, s54, 0x9a10000
	s_addc_u32 s55, s55, 0
	s_lshl_b32 s1, s72, 3
	s_add_u32 s68, s58, s1
	s_addc_u32 s69, s59, 0
	s_add_u32 s68, s68, 0x910000
	s_addc_u32 s69, s69, 0
	s_lshr_b32 s1, s72, 12
	s_add_i32 s1, s1, s0
	s_mul_i32 s1, s1, 0x6000
	s_add_i32 s1, s1, 0x3000
	s_add_u32 s70, s58, s1
	s_addc_u32 s71, s59, 0
	global_load_dwordx4 v[116:119], v42, s[70:71]
	global_load_dwordx4 v[120:123], v42, s[70:71] offset:1024
	global_load_dwordx4 v[124:127], v42, s[70:71] offset:2048
	global_load_dwordx4 v[128:131], v42, s[70:71] offset:3072
	global_load_dwordx4 v[132:135], v43, s[70:71]
	global_load_dwordx4 v[136:139], v43, s[70:71] offset:1024
	global_load_dwordx4 v[140:143], v43, s[70:71] offset:2048
	global_load_dwordx4 v[144:147], v43, s[70:71] offset:3072
	s_add_i32 s73, s72, s44
	s_cmp_gt_i32 s73, s46
	s_cbranch_scc1 .Llnb_np1
	s_lshl_b32 s1, s73, 11
	s_add_u32 s28, s58, s1
	s_addc_u32 s29, s59, 0
	s_add_u32 s28, s28, 0xa10000
	s_addc_u32 s29, s29, 0
	global_load_dwordx2 v[44:45], v41, s[28:29] nt
	global_load_dwordx2 v[46:47], v41, s[28:29] offset:512 nt
	global_load_dwordx2 v[48:49], v41, s[28:29] offset:1024 nt
	global_load_dwordx2 v[50:51], v41, s[28:29] offset:1536 nt
	global_load_dwordx2 v[52:53], v41, s[28:29] offset:2048 nt
	global_load_dwordx2 v[54:55], v41, s[28:29] offset:2560 nt
	global_load_dwordx2 v[56:57], v41, s[28:29] offset:3072 nt
	global_load_dwordx2 v[58:59], v41, s[28:29] offset:3584 nt
	s_waitcnt vmcnt(25)
	s_branch .Llnb_go1

.Llnb_gq1:
	v_pk_add_f32 v[132:133], v[132:133], 1.0 op_sel_hi:[1,0]
	v_pk_add_f32 v[134:135], v[134:135], 1.0 op_sel_hi:[1,0]
	v_pk_add_f32 v[136:137], v[136:137], 1.0 op_sel_hi:[1,0]
	v_pk_add_f32 v[138:139], v[138:139], 1.0 op_sel_hi:[1,0]
	v_pk_add_f32 v[140:141], v[140:141], 1.0 op_sel_hi:[1,0]
	v_pk_add_f32 v[142:143], v[142:143], 1.0 op_sel_hi:[1,0]
	v_pk_add_f32 v[144:145], v[144:145], 1.0 op_sel_hi:[1,0]
	v_pk_add_f32 v[146:147], v[146:147], 1.0 op_sel_hi:[1,0]
	v_pk_fma_f32 v[84:85], v[84:85], v[132:133], v[116:117] op_sel:[0,0,0] op_sel_hi:[1,0,0]
	v_pk_fma_f32 v[86:87], v[86:87], v[132:133], v[116:117] op_sel:[0,1,1] op_sel_hi:[1,1,1]
	v_pk_fma_f32 v[88:89], v[88:89], v[134:135], v[118:119] op_sel:[0,0,0] op_sel_hi:[1,0,0]
	v_pk_fma_f32 v[90:91], v[90:91], v[134:135], v[118:119] op_sel:[0,1,1] op_sel_hi:[1,1,1]
	v_pk_fma_f32 v[92:93], v[92:93], v[136:137], v[120:121] op_sel:[0,0,0] op_sel_hi:[1,0,0]
	v_pk_fma_f32 v[94:95], v[94:95], v[136:137], v[120:121] op_sel:[0,1,1] op_sel_hi:[1,1,1]
	v_pk_fma_f32 v[96:97], v[96:97], v[138:139], v[122:123] op_sel:[0,0,0] op_sel_hi:[1,0,0]
	v_pk_fma_f32 v[98:99], v[98:99], v[138:139], v[122:123] op_sel:[0,1,1] op_sel_hi:[1,1,1]
	v_pk_fma_f32 v[100:101], v[100:101], v[140:141], v[124:125] op_sel:[0,0,0] op_sel_hi:[1,0,0]
	v_pk_fma_f32 v[102:103], v[102:103], v[140:141], v[124:125] op_sel:[0,1,1] op_sel_hi:[1,1,1]
	v_pk_fma_f32 v[104:105], v[104:105], v[142:143], v[126:127] op_sel:[0,0,0] op_sel_hi:[1,0,0]
	v_pk_fma_f32 v[106:107], v[106:107], v[142:143], v[126:127] op_sel:[0,1,1] op_sel_hi:[1,1,1]
	v_pk_fma_f32 v[108:109], v[108:109], v[144:145], v[128:129] op_sel:[0,0,0] op_sel_hi:[1,0,0]
	v_pk_fma_f32 v[110:111], v[110:111], v[144:145], v[128:129] op_sel:[0,1,1] op_sel_hi:[1,1,1]
	v_pk_fma_f32 v[112:113], v[112:113], v[146:147], v[130:131] op_sel:[0,0,0] op_sel_hi:[1,0,0]
	v_pk_fma_f32 v[114:115], v[114:115], v[146:147], v[130:131] op_sel:[0,1,1] op_sel_hi:[1,1,1]
	v_cvt_pk_bf16_f32 v60, v84, v86
	v_cvt_pk_bf16_f32 v61, v88, v90
	v_cvt_pk_bf16_f32 v62, v92, v94
	v_cvt_pk_bf16_f32 v63, v96, v98
	v_cvt_pk_bf16_f32 v64, v100, v102
	v_cvt_pk_bf16_f32 v65, v104, v106
	v_cvt_pk_bf16_f32 v66, v108, v110
	v_cvt_pk_bf16_f32 v67, v112, v114
	v_cvt_pk_bf16_f32 v68, v85, v87
	v_cvt_pk_bf16_f32 v69, v89, v91
	v_cvt_pk_bf16_f32 v70, v93, v95
	v_cvt_pk_bf16_f32 v71, v97, v99
	v_cvt_pk_bf16_f32 v72, v101, v103
	v_cvt_pk_bf16_f32 v73, v105, v107
	v_cvt_pk_bf16_f32 v74, v109, v111
	v_cvt_pk_bf16_f32 v75, v113, v115
	global_store_dwordx2 v41, v[60:61], s[54:55]
	global_store_dwordx2 v41, v[62:63], s[54:55] offset:512
	global_store_dwordx2 v41, v[64:65], s[54:55] offset:1024
	global_store_dwordx2 v41, v[66:67], s[54:55] offset:1536
	global_store_dwordx2 v41, v[68:69], s[54:55] offset:2048
	global_store_dwordx2 v41, v[70:71], s[54:55] offset:2560
	global_store_dwordx2 v41, v[72:73], s[54:55] offset:3072
	global_store_dwordx2 v41, v[74:75], s[54:55] offset:3584
	s_cmp_gt_i32 s73, s46
	s_cbranch_scc1 .Llnb_exit
	s_mov_b32 s72, s73
	s_lshl_b32 s1, s72, 11
	s_add_u32 s54, s58, s1
	s_addc_u32 s55, s59, 0
	s_add_u32 s54, s54, 0x9a10000
	s_addc_u32 s55, s55, 0
	s_lshl_b32 s1, s72, 3
	s_add_u32 s68, s58, s1
	s_addc_u32 s69, s59, 0
	s_add_u32 s68, s68, 0x910000
	s_addc_u32 s69, s69, 0
	s_lshr_b32 s1, s72, 12
	s_add_i32 s1, s1, s0
	s_mul_i32 s1, s1, 0x6000
	s_add_i32 s1, s1, 0x3000
	s_add_u32 s70, s58, s1
	s_addc_u32 s71, s59, 0
	global_load_dwordx4 v[116:119], v42, s[70:71]
	global_load_dwordx4 v[120:123], v42, s[70:71] offset:1024
	global_load_dwordx4 v[124:127], v42, s[70:71] offset:2048
	global_load_dwordx4 v[128:131], v42, s[70:71] offset:3072
	global_load_dwordx4 v[132:135], v43, s[70:71]
	global_load_dwordx4 v[136:139], v43, s[70:71] offset:1024
	global_load_dwordx4 v[140:143], v43, s[70:71] offset:2048
	global_load_dwordx4 v[144:147], v43, s[70:71] offset:3072
	s_add_i32 s73, s72, s44
	s_cmp_gt_i32 s73, s46
	s_cbranch_scc1 .Llnb_np2
	s_lshl_b32 s1, s73, 11
	s_add_u32 s28, s58, s1
	s_addc_u32 s29, s59, 0
	s_add_u32 s28, s28, 0xa10000
	s_addc_u32 s29, s29, 0
	global_load_dwordx2 v[60:61], v41, s[28:29] nt
	global_load_dwordx2 v[62:63], v41, s[28:29] offset:512 nt
	global_load_dwordx2 v[64:65], v41, s[28:29] offset:1024 nt
	global_load_dwordx2 v[66:67], v41, s[28:29] offset:1536 nt
	global_load_dwordx2 v[68:69], v41, s[28:29] offset:2048 nt
	global_load_dwordx2 v[70:71], v41, s[28:29] offset:2560 nt
	global_load_dwordx2 v[72:73], v41, s[28:29] offset:3072 nt
	global_load_dwordx2 v[74:75], v41, s[28:29] offset:3584 nt
	s_waitcnt vmcnt(25)
	s_branch .Llnb_go2

.Llnb_exit:
.LBB0_279:
	s_or_b64 exec, exec, s[42:43]
